# code placement: MLA and NSA tile-loop heads also aligned to 64 bytes
# baseline (speedup 1.0000x reference)
; #define LAS __attribute__((address_space(3)))
; DI void mla_unit(const Params& p, LAS unsigned char* lds, int b, int h, int qb, int tid) {
;     unsigned char* ws = p.ws;
;     const bf16_t* QMLA = (const bf16_t*)(ws + OFF_QMLA); const bf16_t* KNOPE = (const bf16_t*)(ws + OFF_KNOPE);
;     const bf16_t* KROPE = (const bf16_t*)(ws + OFF_KROPE); const bf16_t* VT = (const bf16_t*)(ws + OFF_VT);
;     bf16_t* MIX = (bf16_t*)(ws + OFF_MIX);
;     const int lane = tid & 63, w = __builtin_amdgcn_readfirstlane(tid >> 6), c = lane & 31, hi = lane >> 5;
;     const int q0 = qb * 256, qw0 = q0 + 32 * w, qpos = qw0 + c;
;     const size_t tokb = (size_t)b * S_;
;     bf16x8 qf[12];
;     { const bf16_t* qp = QMLA + (tokb + qpos) * 1536 + h * 192 + 8 * hi;
; #pragma unroll
;       for (int st = 0; st < 12; ++st) qf[st] = *(const bf16x8*)(qp + 16 * st); }
;     f32x16 o[4];
; #pragma unroll
;     for (int db = 0; db < 4; ++db)
; #pragma unroll
;         for (int i = 0; i < 16; ++i) o[db][i] = 0.f;
;     float m = -1e20f, l = 0.f;
;     const int nkt = 4 * qb + 4;
;     u32x4 r[5];
;     __syncthreads();
;     mla_load(KNOPE, KROPE, VT, h, tokb, 0, r, tid); mla_store(lds, r, tid);
;     __syncthreads();
; __global__ void __launch_bounds__(NTHREADS, 2) fwd_megakernel(Params p) {
;     ...
;                 if (tid == 0) QU[0] = (int)atomicAdd(ctl + qq * 16, 1u);
;                 __syncthreads();
;                 const int qi_ = QU[0];
;                 if (qi_ >= 128) break;
;                 const int pr_ = qi_ >> 6, r_ = qi_ & 63;
;                 const int qb = 31 - (r_ >> 1), bh = qq + 8 * (2 * pr_ + (r_ & 1));
.LBB0_618:
	s_or_b64 exec, exec, s[2:3]
	v_mov_b32_e32 v1, s1
	s_waitcnt lgkmcnt(0)
	s_barrier
	ds_read_b32 v1, v1
	s_movk_i32 s2, 0x7f
	s_waitcnt lgkmcnt(0)
	v_cmp_lt_i32_e32 vcc, s2, v1
	v_readfirstlane_b32 s4, v1
	s_mov_b64 s[2:3], -1
	s_cbranch_vccnz .LBB0_613
	s_not_b32 s2, s4
	s_bfe_u32 s8, s2, 0x50001
	s_ashr_i32 s2, s4, 5
	s_and_b32 s2, s2, -2
	s_and_b32 s3, s4, 1
	s_or_b32 s2, s2, s3
	v_readfirstlane_b32 s3, v0
	s_ashr_i32 s3, s3, 1
	s_lshl_b32 s79, s8, 8
	s_and_b32 s58, s3, 0xffffffe0
	v_and_b32_e32 v1, 31, v0
	s_add_i32 s58, s58, s79
	v_or_b32_e32 v2, s58, v1
	s_ashr_i32 s3, s2, 31
	s_lshl_b64 s[4:5], s[2:3], 13
	v_ashrrev_i32_e32 v3, 31, v2
	v_lshl_add_u64 v[150:151], s[4:5], 0, v[2:3]
	v_mov_b64_e32 v[4:5], s[70:71]
	v_add_u32_e32 v17, 0x200, v0
	v_bfe_u32 v16, v0, 5, 1
	v_mad_u64_u32 v[4:5], s[6:7], v150, s12, v[4:5]
	v_ashrrev_i32_e32 v6, 4, v0
	v_ashrrev_i32_e32 v10, 4, v17
	v_mad_i32_i24 v5, v151, s12, v5
	v_lshlrev_b32_e32 v148, 4, v16
	v_lshlrev_b32_e32 v3, 4, v0
	v_ashrrev_i32_e32 v7, 31, v6
	v_ashrrev_i32_e32 v11, 31, v10
	v_lshl_add_u64 v[4:5], v[4:5], 0, v[148:149]
	v_and_b32_e32 v152, 0xf0, v3
	v_mov_b32_e32 v153, v149
	v_lshl_add_u64 v[8:9], s[4:5], 0, v[6:7]
	v_lshl_add_u64 v[12:13], s[4:5], 0, v[10:11]
	global_load_dwordx4 v[80:83], v[4:5], off
	global_load_dwordx4 v[84:87], v[4:5], off offset:32
	global_load_dwordx4 v[88:91], v[4:5], off offset:64
	global_load_dwordx4 v[92:95], v[4:5], off offset:96
	global_load_dwordx4 v[96:99], v[4:5], off offset:128
	global_load_dwordx4 v[100:103], v[4:5], off offset:160
	global_load_dwordx4 v[104:107], v[4:5], off offset:192
	global_load_dwordx4 v[108:111], v[4:5], off offset:224
	global_load_dwordx4 v[112:115], v[4:5], off offset:256
	global_load_dwordx4 v[116:119], v[4:5], off offset:288
	global_load_dwordx4 v[120:123], v[4:5], off offset:320
	global_load_dwordx4 v[124:127], v[4:5], off offset:352
	v_lshl_add_u64 v[4:5], s[72:73], 0, v[152:153]
	v_lshlrev_b64 v[8:9], 11, v[8:9]
	v_lshlrev_b64 v[12:13], 11, v[12:13]
	v_lshl_add_u64 v[8:9], v[4:5], 0, v[8:9]
	v_lshl_add_u64 v[4:5], v[4:5], 0, v[12:13]
	s_barrier
	global_load_dwordx4 v[128:131], v[8:9], off
	global_load_dwordx4 v[132:135], v[4:5], off
	v_ashrrev_i32_e32 v4, 3, v0
	s_lshl_b32 s59, s8, 2
	v_ashrrev_i32_e32 v5, 31, v4
	s_add_i32 s59, s59, 4
	v_lshl_add_u64 v[8:9], s[4:5], 0, v[4:5]
	s_lshl_b64 s[4:5], s[2:3], 14
	v_lshlrev_b64 v[8:9], 7, v[8:9]
	s_add_u32 s6, s52, s4
	v_add_u32_e32 v14, s42, v4
	v_lshl_add_u64 v[8:9], s[54:55], 0, v[8:9]
	v_and_b32_e32 v154, 0x70, v3
	v_mov_b32_e32 v155, v149
	s_addc_u32 s7, s53, s5
	v_ashrrev_i32_e32 v15, 31, v14
	v_lshl_add_u64 v[8:9], v[8:9], 0, v[154:155]
	v_lshl_add_u64 v[12:13], s[6:7], 0, v[154:155]
	v_lshlrev_b64 v[14:15], 16, v[14:15]
	v_lshl_add_u64 v[14:15], v[12:13], 0, v[14:15]
	global_load_dwordx4 v[136:139], v[8:9], off
	global_load_dwordx4 v[140:143], v[14:15], off
	v_ashrrev_i32_e32 v8, 3, v17
	v_add_u32_e32 v14, s42, v8
	v_ashrrev_i32_e32 v15, 31, v14
	v_lshlrev_b64 v[14:15], 16, v[14:15]
	v_lshl_add_u64 v[12:13], v[12:13], 0, v[14:15]
	global_load_dwordx4 v[144:147], v[12:13], off
	v_mul_lo_u32 v171, v6, s13
	v_add_u32_e32 v3, 0, v152
	v_mul_lo_u32 v173, v10, s13
	v_add_u32_e32 v9, v3, v171
	v_add_u32_e32 v3, v3, v173
	v_mul_lo_u32 v172, v4, s13
	v_mul_lo_u32 v175, v4, s33
	v_mul_lo_u32 v176, v8, s33
	s_or_b32 s78, s58, 31
	v_lshlrev_b32_e32 v174, 2, v16
	s_add_u32 s4, s4, s43
	v_sub_u32_e32 v179, v2, v174
	s_addc_u32 s5, s5, s48
	v_and_b32_e32 v0, 15, v0
	v_mul_u32_u24_e32 v177, 0x88, v1
	v_mul_u32_u24_e32 v178, 0x190, v1
	v_lshlrev_b32_e32 v0, 4, v0
	v_mov_b32_e32 v1, v149
	v_mov_b32_e32 v14, v149
	v_mov_b32_e32 v15, v149
	v_lshlrev_b32_e32 v153, 3, v16
	v_mov_b32_e32 v12, v149
	v_mov_b32_e32 v13, v149
	s_mov_b32 s80, 0
	v_mov_b32_e32 v180, 0xe0ad78ec
	v_mov_b32_e32 v240, 0
	v_mov_b32_e32 v241, 0
	v_mov_b32_e32 v242, 0
	v_mov_b32_e32 v243, 0
	v_mov_b32_e32 v244, 0
	v_mov_b32_e32 v245, 0
	v_mov_b32_e32 v246, 0
	v_mov_b32_e32 v247, 0
	v_mov_b32_e32 v248, 0
	v_mov_b32_e32 v249, 0
	v_mov_b32_e32 v250, 0
	v_mov_b32_e32 v251, 0
	v_mov_b32_e32 v252, 0
	v_mov_b32_e32 v253, 0
	v_mov_b32_e32 v254, 0
	v_mov_b32_e32 v255, 0
	v_mov_b32_e32 v235, 0xe0ad78ec
	s_waitcnt vmcnt(4)
	ds_write_b128 v9, v[128:131]
	s_waitcnt vmcnt(3)
	ds_write_b128 v3, v[132:135]
	v_add_u32_e32 v3, 0, v154
	v_add_u32_e32 v9, v3, v172
	s_waitcnt vmcnt(2)
	ds_write_b128 v9, v[136:139] offset:256
	v_add3_u32 v9, v3, v175, s40
	v_add3_u32 v3, v3, v176, s40
	s_waitcnt vmcnt(1)
	ds_write2_b64 v9, v[140:141], v[142:143] offset1:1
	v_ashrrev_i32_e32 v9, 31, v8
	s_waitcnt vmcnt(0)
	ds_write2_b64 v3, v[144:145], v[146:147] offset1:1
	v_lshlrev_b64 v[2:3], 16, v[4:5]
	v_lshl_add_u64 v[2:3], s[4:5], 0, v[2:3]
	v_lshl_add_u64 v[156:157], v[2:3], 0, v[154:155]
	v_lshlrev_b64 v[2:3], 16, v[8:9]
	v_lshl_add_u64 v[2:3], s[4:5], 0, v[2:3]
	s_lshl_b64 s[4:5], s[2:3], 20
	s_add_u32 s4, s4, 0x2f002000
	s_addc_u32 s5, s5, 0
	s_lshl_b64 s[2:3], s[2:3], 24
	v_lshl_add_u64 v[158:159], v[2:3], 0, v[154:155]
	v_lshlrev_b64 v[2:3], 7, v[4:5]
	s_add_u32 s2, s49, s2
	v_lshl_add_u64 v[160:161], s[4:5], 0, v[2:3]
	s_addc_u32 s3, 0, s3
	v_lshlrev_b64 v[2:3], 11, v[10:11]
	v_lshl_add_u64 v[2:3], s[2:3], 0, v[2:3]
	v_lshl_add_u64 v[162:163], v[2:3], 0, v[0:1]
	v_lshlrev_b64 v[2:3], 11, v[6:7]
	v_lshl_add_u64 v[2:3], s[2:3], 0, v[2:3]
	v_lshl_add_u64 v[164:165], v[2:3], 0, v[0:1]
	v_mov_b32_e32 v0, v149
	v_mov_b32_e32 v2, v149
	v_mov_b32_e32 v3, v149
	v_mov_b32_e32 v4, v149
	v_mov_b32_e32 v5, v149
	v_mov_b32_e32 v6, v149
	v_mov_b32_e32 v7, v149
	v_mov_b32_e32 v8, v149
	v_mov_b32_e32 v9, v149
	v_mov_b32_e32 v10, v149
	v_mov_b32_e32 v11, v149
	v_mov_b64_e32 v[30:31], v[14:15]
	v_mov_b64_e32 v[46:47], v[14:15]
	v_mov_b64_e32 v[62:63], v[14:15]
	v_or_b32_e32 v160, v160, v154
	s_addk_i32 s79, 0x100
	v_mov_b32_e32 v155, 0
	v_mov_b64_e32 v[28:29], v[12:13]
	v_mov_b64_e32 v[26:27], v[10:11]
	v_mov_b64_e32 v[24:25], v[8:9]
	v_mov_b64_e32 v[22:23], v[6:7]
	v_mov_b64_e32 v[20:21], v[4:5]
	v_mov_b64_e32 v[18:19], v[2:3]
	v_mov_b64_e32 v[16:17], v[0:1]
	v_mov_b64_e32 v[44:45], v[12:13]
	v_mov_b64_e32 v[42:43], v[10:11]
	v_mov_b64_e32 v[40:41], v[8:9]
	v_mov_b64_e32 v[38:39], v[6:7]
	v_mov_b64_e32 v[36:37], v[4:5]
	v_mov_b64_e32 v[34:35], v[2:3]
	v_mov_b64_e32 v[32:33], v[0:1]
	v_mov_b64_e32 v[60:61], v[12:13]
	v_mov_b64_e32 v[58:59], v[10:11]
	v_mov_b64_e32 v[56:57], v[8:9]
	v_mov_b64_e32 v[54:55], v[6:7]
	v_mov_b64_e32 v[52:53], v[4:5]
	v_mov_b64_e32 v[50:51], v[2:3]
	v_mov_b64_e32 v[48:49], v[0:1]
	s_mov_b32 s2, 0
	s_waitcnt lgkmcnt(0)
	s_barrier
	.p2align	6

; #define LAS __attribute__((address_space(3)))
; #define ST_V(base, v) do { LAS unsigned char* vp_ = (base) + voff; *(LAS u32x2*)vp_ = (u32x2){(v).x, (v).y}; *(LAS u32x2*)(vp_ + 8) = (u32x2){(v).z, (v).w}; } while (0)
; DI void nsa_unit(const Params& p, LAS unsigned char* lds, unsigned char* ldsg, int bg, int qt, int tid) {
;     ...
;     const int kq = tid >> 3, kch = tid & 7;
;     const int toff = kq * 144 + kch * 16, voff = 9216 + kq * 136 + kch * 16;
;     ...
;     {
;         const int nl = NL[0];
;         const bf16_t* Ksrc = PROJ + (tokb + kq) * NPROJ + 2112 + g * 64 + 8 * kch;
;         const bf16_t* Vsrc = VST + ((size_t)(bg * 64 + kq)) * S_ + 8 * kch;
;         f32x16 o[2];
; #pragma unroll
;         for (int db = 0; db < 2; ++db)
; #pragma unroll
;             for (int i = 0; i < 16; ++i) o[db][i] = 0.f;
;         float m = -1e20f, l = 0.f;
;         u32x4 rk1, rv1, rk2, rv2;
;         { const int nb = LIST[0]; rk1 = *(const u32x4*)(Ksrc + (size_t)(64 * nb) * NPROJ); rv1 = *(const u32x4*)(Vsrc + 64 * nb); }
;         *(LAS u32x4*)(lds + toff) = rk1; ST_V(lds, rv1);
;         if (nl > 1) { const int nb = LIST[1]; rk1 = *(const u32x4*)(Ksrc + (size_t)(64 * nb) * NPROJ); rv1 = *(const u32x4*)(Vsrc + 64 * nb); }
;         __syncthreads();
;         int cb = 0;
;         for (int i = 0; i < nl; ++i) {
.LBB0_818:
	s_movk_i32 s2, 0x88
	s_cmp_lt_i32 s8, 1
	v_mul_u32_u24_e32 v15, 0x88, v68
	v_mad_u32_u24 v176, v68, s2, v168
	s_waitcnt lgkmcnt(0)
	s_barrier
	s_cbranch_scc1 .LBB0_839
	v_or_b32_e32 v10, s49, v67
	s_add_i32 s2, 0, 0x26400
	v_lshl_add_u32 v113, v10, 4, s2
	v_lshlrev_b32_e32 v10, 2, v114
	v_mov_b32_e32 v175, 0
	v_sub_u32_e32 v117, v150, v10
	v_mov_b32_e32 v153, v152
	v_mov_b32_e32 v118, 0xe0ad78ec
	v_mov_b32_e32 v252, 0xe0ad78ec
	v_mov_b32_e32 v248, 0
	s_mov_b32 s9, 0
	v_readlane_b32 s10, v234, 35
	s_mov_b32 s11, 0
	v_mov_b32_e32 v48, 0
	v_mov_b32_e32 v49, v175
	v_mov_b32_e32 v50, v175
	v_mov_b32_e32 v51, v175
	v_mov_b32_e32 v52, v175
	v_mov_b32_e32 v53, v175
	v_mov_b32_e32 v54, v175
	v_mov_b32_e32 v55, v175
	v_mov_b32_e32 v56, v175
	v_mov_b32_e32 v57, v175
	v_mov_b32_e32 v58, v175
	v_mov_b32_e32 v59, v175
	v_mov_b32_e32 v60, v175
	v_mov_b32_e32 v61, v175
	v_mov_b32_e32 v62, v175
	v_mov_b32_e32 v63, v175
	v_mov_b32_e32 v64, v175
	v_mov_b32_e32 v65, v175
	v_mov_b32_e32 v66, v175
	v_mov_b32_e32 v67, v175
	v_mov_b32_e32 v68, v175
	v_mov_b32_e32 v69, v175
	v_mov_b32_e32 v70, v175
	v_mov_b32_e32 v71, v175
	v_mov_b32_e32 v72, v175
	v_mov_b32_e32 v73, v175
	v_mov_b32_e32 v74, v175
	v_mov_b32_e32 v75, v175
	v_mov_b32_e32 v76, v175
	v_mov_b32_e32 v77, v175
	v_mov_b32_e32 v78, v175
	v_mov_b32_e32 v79, v175
	.p2align	6

; DI void nsa_unit(const Params& p, LAS unsigned char* lds, unsigned char* ldsg, int bg, int qt, int tid) {
;     ...
;         for (int kt = kt_lo; kt <= kt_hi; ++kt) {
;             if (kt + 2 <= kt_hi) { rk2 = *(const u32x4*)(Ksrc + (size_t)(64 * (kt + 2)) * NPROJ); rv2 = *(const u32x4*)(Vsrc + 64 * (kt + 2)); }
.LBB0_845:
	s_add_i32 s66, s8, 0x80
	v_mad_u64_u32 v[10:11], s[2:3], s66, v170, v[156:157]
	v_lshl_add_u64 v[12:13], s[66:67], 1, v[158:159]
	global_load_dwordx4 v[144:147], v[10:11], off
	s_nop 0
	global_load_dwordx4 v[10:13], v[12:13], off
	.p2align	6
